# speedup vs baseline: 1.0212x; 1.0006x over previous
; template <int EPI, int AMAP, int KOFFMODE, int K>
; __device__ __forceinline__ void gemm_phase(unsigned char* smem, const bf16_t* A, int lda, const bf16_t* Bt, int NT, const EpiArgs& ea) {
;     ...
;         f32x16 acc[4][2];
; #pragma unroll
;         for (int i = 0; i < 4; ++i)
; #pragma unroll
;             for (int j = 0; j < 2; ++j)
; #pragma unroll
;                 for (int r = 0; r < 16; ++r) acc[i][j][r] = 0.f;
;         for (int kt = 0; kt < nk; ++kt) {
;             if (kt + 1 < nk) GEMM_DMA(m0, n0, kt + 1, cur ^ 1);
;             else if (have_next) GEMM_DMA(m0n, n0n, 0, cur ^ 1);
;             const unsigned char* Ac = smem + cur * STGB + (wm * 128 + l31) * 128;
;             const unsigned char* Bc = smem + cur * STGB + 32768 + (wn * 64 + l31) * 128;
;             bf16x8 fa[2][4], fb[2][2];
;             fb[0][0] = *(const bf16x8*)(Bc + (((0) ^ yz) & 7) * 16);
;             fb[0][1] = *(const bf16x8*)(Bc + 32 * 128 + (((0) ^ yz) & 7) * 16);
; #pragma unroll
;             for (int i = 0; i < 4; ++i) fa[0][i] = *(const bf16x8*)(Ac + i * 32 * 128 + (((0) ^ yz) & 7) * 16);
; #pragma unroll
;             for (int s = 0; s < 4; ++s) {
;                 if (s < 3) {
;                     const int o_ = (((2 * (s + 1)) ^ yz) & 7) * 16;
;                     fb[(s + 1) & 1][0] = *(const bf16x8*)(Bc + o_);
;                     fb[(s + 1) & 1][1] = *(const bf16x8*)(Bc + 32 * 128 + o_);
; #pragma unroll
;                     for (int i = 0; i < 4; ++i) fa[(s + 1) & 1][i] = *(const bf16x8*)(Ac + i * 32 * 128 + o_);
;                 }
; #pragma unroll
;                 for (int i = 0; i < 4; ++i) {
;                     acc[i][0] = __builtin_amdgcn_mfma_f32_32x32x16_bf16(fa[s & 1][i], fb[s & 1][0], acc[i][0], 0, 0, 0);
;                     acc[i][1] = __builtin_amdgcn_mfma_f32_32x32x16_bf16(fa[s & 1][i], fb[s & 1][1], acc[i][1], 0, 0, 0);
;                 }
;                 __builtin_amdgcn_sched_barrier(0);
;             }
;             if (kt + 1 < nk) asm volatile("s_waitcnt vmcnt(0)" ::: "memory");
;             __builtin_amdgcn_s_barrier();
;             cur ^= 1;
;         }
.LBB0_460:
	v_add_u32_e32 v0, s10, v142
	v_mad_i64_i32 v[136:137], s[4:5], v0, s37, v[134:135]
	v_add_u32_e32 v0, s11, v142
	v_mad_i64_i32 v[138:139], s[4:5], v0, s37, v[134:135]
	v_mov_b32_e32 v2, 0
	s_mov_b64 s[4:5], 0
	s_mov_b32 s13, s9
	v_mov_b32_e32 v3, v2
	v_mov_b32_e32 v4, v2
	v_mov_b32_e32 v5, v2
	v_mov_b32_e32 v6, v2
	v_mov_b32_e32 v7, v2
	v_mov_b32_e32 v8, v2
	v_mov_b32_e32 v9, v2
	v_mov_b32_e32 v10, v2
	v_mov_b32_e32 v11, v2
	v_mov_b32_e32 v12, v2
	v_mov_b32_e32 v13, v2
	v_mov_b32_e32 v14, v2
	v_mov_b32_e32 v15, v2
	v_mov_b32_e32 v16, v2
	v_mov_b32_e32 v17, v2
	v_mov_b32_e32 v18, v2
	v_mov_b32_e32 v19, v2
	v_mov_b32_e32 v20, v2
	v_mov_b32_e32 v21, v2
	v_mov_b32_e32 v22, v2
	v_mov_b32_e32 v23, v2
	v_mov_b32_e32 v24, v2
	v_mov_b32_e32 v25, v2
	v_mov_b32_e32 v26, v2
	v_mov_b32_e32 v27, v2
	v_mov_b32_e32 v28, v2
	v_mov_b32_e32 v29, v2
	v_mov_b32_e32 v30, v2
	v_mov_b32_e32 v31, v2
	v_mov_b32_e32 v32, v2
	v_mov_b32_e32 v33, v2
	v_mov_b32_e32 v34, v2
	v_mov_b32_e32 v35, v2
	v_mov_b32_e32 v36, v2
	v_mov_b32_e32 v37, v2
	v_mov_b32_e32 v38, v2
	v_mov_b32_e32 v39, v2
	v_mov_b32_e32 v40, v2
	v_mov_b32_e32 v41, v2
	v_mov_b32_e32 v42, v2
	v_mov_b32_e32 v43, v2
	v_mov_b32_e32 v44, v2
	v_mov_b32_e32 v45, v2
	v_mov_b32_e32 v46, v2
	v_mov_b32_e32 v47, v2
	v_mov_b32_e32 v48, v2
	v_mov_b32_e32 v49, v2
	v_mov_b32_e32 v50, v2
	v_mov_b32_e32 v51, v2
	v_mov_b32_e32 v52, v2
	v_mov_b32_e32 v53, v2
	v_mov_b32_e32 v54, v2
	v_mov_b32_e32 v55, v2
	v_mov_b32_e32 v56, v2
	v_mov_b32_e32 v57, v2
	v_mov_b32_e32 v58, v2
	v_mov_b32_e32 v59, v2
	v_mov_b32_e32 v60, v2
	v_mov_b32_e32 v61, v2
	v_mov_b32_e32 v62, v2
	v_mov_b32_e32 v63, v2
	v_mov_b32_e32 v64, v2
	v_mov_b32_e32 v65, v2
	v_mov_b32_e32 v66, v2
	v_mov_b32_e32 v67, v2
	v_mov_b32_e32 v68, v2
	v_mov_b32_e32 v69, v2
	v_mov_b32_e32 v70, v2
	v_mov_b32_e32 v71, v2
	v_mov_b32_e32 v72, v2
	v_mov_b32_e32 v73, v2
	v_mov_b32_e32 v74, v2
	v_mov_b32_e32 v75, v2
	v_mov_b32_e32 v76, v2
	v_mov_b32_e32 v77, v2
	v_mov_b32_e32 v78, v2
	v_mov_b32_e32 v79, v2
	v_mov_b32_e32 v80, v2
	v_mov_b32_e32 v81, v2
	v_mov_b32_e32 v82, v2
	v_mov_b32_e32 v83, v2
	v_mov_b32_e32 v84, v2
	v_mov_b32_e32 v85, v2
	v_mov_b32_e32 v86, v2
	v_mov_b32_e32 v87, v2
	v_mov_b32_e32 v88, v2
	v_mov_b32_e32 v89, v2
	v_mov_b32_e32 v90, v2
	v_mov_b32_e32 v91, v2
	v_mov_b32_e32 v92, v2
	v_mov_b32_e32 v93, v2
	v_mov_b32_e32 v94, v2
	v_mov_b32_e32 v95, v2
	v_mov_b32_e32 v96, v2
	v_mov_b32_e32 v97, v2
	v_mov_b32_e32 v98, v2
	v_mov_b32_e32 v99, v2
	v_mov_b32_e32 v100, v2
	v_mov_b32_e32 v101, v2
	v_mov_b32_e32 v102, v2
	v_mov_b32_e32 v103, v2
	v_mov_b32_e32 v104, v2
	v_mov_b32_e32 v105, v2
	v_mov_b32_e32 v106, v2
	v_mov_b32_e32 v107, v2
	v_mov_b32_e32 v108, v2
	v_mov_b32_e32 v109, v2
	v_mov_b32_e32 v110, v2
	v_mov_b32_e32 v111, v2
	v_mov_b32_e32 v112, v2
	v_mov_b32_e32 v113, v2
	v_mov_b32_e32 v114, v2
	v_mov_b32_e32 v115, v2
	v_mov_b32_e32 v116, v2
	v_mov_b32_e32 v117, v2
	v_mov_b32_e32 v118, v2
	v_mov_b32_e32 v119, v2
	v_mov_b32_e32 v120, v2
	v_mov_b32_e32 v121, v2
	v_mov_b32_e32 v122, v2
	v_mov_b32_e32 v123, v2
	v_mov_b32_e32 v124, v2
	v_mov_b32_e32 v125, v2
	v_mov_b32_e32 v126, v2
	v_mov_b32_e32 v127, v2
	v_mov_b32_e32 v128, v2
	v_mov_b32_e32 v129, v2
	s_lshl_b32 vcc_lo, s13, 16
	v_add3_u32 v155, vcc_lo, v150, v149
	v_add_u32_e32 v155, v155, v151
	v_add3_u32 v0, vcc_lo, v147, v149
	v_add_u32_e32 v0, v0, v151
	ds_read_b128 v[156:159], v155 offset:32768
	ds_read_b128 v[160:163], v155 offset:36864
	ds_read_b128 v[192:195], v0
	ds_read_b128 v[196:199], v0 offset:4096
	ds_read_b128 v[200:203], v0 offset:8192
	ds_read_b128 v[204:207], v0 offset:12288
.LBB0_461:
	s_mov_b32 s9, s13
	s_lshl_b32 s13, s9, 16
	s_xor_b32 s12, s13, 0x10000
	v_readfirstlane_b32 vcc_lo, v143
	s_nop 0
	s_add_u32 vcc_lo, vcc_lo, s12
	v_add3_u32 v155, s13, v150, v149
	v_add_u32_e32 v155, v155, v152
	v_add3_u32 v0, s13, v147, v149
	v_add_u32_e32 v0, v0, v152
	ds_read_b128 v[208:211], v155 offset:32768
	ds_read_b128 v[212:215], v155 offset:36864
	s_waitcnt lgkmcnt(5)
	v_mfma_f32_32x32x16_bf16 v[114:129], v[192:195], v[156:159], v[114:129]
	s_add_u32 s14, s4, 0xb240080
	s_addc_u32 s15, s5, 0
	s_mov_b32 m0, vcc_lo
	v_lshl_add_u64 v[164:165], v[136:137], 0, s[14:15]
	global_load_lds_dwordx4 v[164:165], off
	v_mfma_f32_32x32x16_bf16 v[98:113], v[192:195], v[160:163], v[98:113]
	s_add_u32 s14, s4, 0xb270080
	s_addc_u32 s15, s5, 0
	s_add_u32 m0, vcc_lo, 0x2000
	v_lshl_add_u64 v[164:165], v[136:137], 0, s[14:15]
	global_load_lds_dwordx4 v[164:165], off
	ds_read_b128 v[192:195], v0
	s_waitcnt lgkmcnt(5)
	v_mfma_f32_32x32x16_bf16 v[82:97], v[196:199], v[156:159], v[82:97]
	s_add_u32 s14, s4, 0xb2a0080
	s_addc_u32 s15, s5, 0
	s_add_u32 m0, vcc_lo, 0x4000
	v_lshl_add_u64 v[164:165], v[136:137], 0, s[14:15]
	global_load_lds_dwordx4 v[164:165], off
	v_mfma_f32_32x32x16_bf16 v[66:81], v[196:199], v[160:163], v[66:81]
	s_add_u32 s14, s4, 0xb2d0080
	s_addc_u32 s15, s5, 0
	s_add_u32 m0, vcc_lo, 0x6000
	v_lshl_add_u64 v[164:165], v[136:137], 0, s[14:15]
	global_load_lds_dwordx4 v[164:165], off
	ds_read_b128 v[196:199], v0 offset:4096
	s_waitcnt lgkmcnt(5)
	v_mfma_f32_32x32x16_bf16 v[50:65], v[200:203], v[156:159], v[50:65]
	s_add_u32 s14, s4, 0xb00080
	s_addc_u32 s15, s5, 0
	s_add_u32 m0, vcc_lo, 0x8000
	v_lshl_add_u64 v[164:165], v[138:139], 0, s[14:15]
	global_load_lds_dwordx4 v[164:165], off
	v_mfma_f32_32x32x16_bf16 v[34:49], v[200:203], v[160:163], v[34:49]
	s_add_u32 s14, s4, 0xb30080
	s_addc_u32 s15, s5, 0
	s_add_u32 m0, vcc_lo, 0xa000
	v_lshl_add_u64 v[164:165], v[138:139], 0, s[14:15]
	global_load_lds_dwordx4 v[164:165], off
	ds_read_b128 v[200:203], v0 offset:8192
	s_waitcnt lgkmcnt(5)
; template <int EPI, int AMAP, int KOFFMODE, int K>
; __device__ __forceinline__ void gemm_phase(unsigned char* smem, const bf16_t* A, int lda, const bf16_t* Bt, int NT, const EpiArgs& ea) {
;     ...
;         for (int kt = 0; kt < nk; ++kt) {
;             if (kt + 1 < nk) GEMM_DMA(m0, n0, kt + 1, cur ^ 1);
;             else if (have_next) GEMM_DMA(m0n, n0n, 0, cur ^ 1);
;             const unsigned char* Ac = smem + cur * STGB + (wm * 128 + l31) * 128;
;             const unsigned char* Bc = smem + cur * STGB + 32768 + (wn * 64 + l31) * 128;
;             bf16x8 fa[2][4], fb[2][2];
;             fb[0][0] = *(const bf16x8*)(Bc + (((0) ^ yz) & 7) * 16);
;             fb[0][1] = *(const bf16x8*)(Bc + 32 * 128 + (((0) ^ yz) & 7) * 16);
; #pragma unroll
;             for (int i = 0; i < 4; ++i) fa[0][i] = *(const bf16x8*)(Ac + i * 32 * 128 + (((0) ^ yz) & 7) * 16);
; #pragma unroll
;             for (int s = 0; s < 4; ++s) {
;                 if (s < 3) {
;                     const int o_ = (((2 * (s + 1)) ^ yz) & 7) * 16;
;                     fb[(s + 1) & 1][0] = *(const bf16x8*)(Bc + o_);
;                     fb[(s + 1) & 1][1] = *(const bf16x8*)(Bc + 32 * 128 + o_);
; #pragma unroll
;                     for (int i = 0; i < 4; ++i) fa[(s + 1) & 1][i] = *(const bf16x8*)(Ac + i * 32 * 128 + o_);
;                 }
; #pragma unroll
;                 for (int i = 0; i < 4; ++i) {
;                     acc[i][0] = __builtin_amdgcn_mfma_f32_32x32x16_bf16(fa[s & 1][i], fb[s & 1][0], acc[i][0], 0, 0, 0);
;                     acc[i][1] = __builtin_amdgcn_mfma_f32_32x32x16_bf16(fa[s & 1][i], fb[s & 1][1], acc[i][1], 0, 0, 0);
;                 }
;                 __builtin_amdgcn_sched_barrier(0);
;             }
;             if (kt + 1 < nk) asm volatile("s_waitcnt vmcnt(0)" ::: "memory");
;             __builtin_amdgcn_s_barrier();
;             cur ^= 1;
;         }
	v_mfma_f32_32x32x16_bf16 v[18:33], v[204:207], v[156:159], v[18:33]
	s_add_u32 s14, s4, 0xb60080
	s_addc_u32 s15, s5, 0
	s_add_u32 m0, vcc_lo, 0xc000
	v_lshl_add_u64 v[164:165], v[138:139], 0, s[14:15]
	global_load_lds_dwordx4 v[164:165], off
	v_mfma_f32_32x32x16_bf16 v[2:17], v[204:207], v[160:163], v[2:17]
	s_add_u32 s14, s4, 0xb90080
	s_addc_u32 s15, s5, 0
	s_add_u32 m0, vcc_lo, 0xe000
	v_lshl_add_u64 v[164:165], v[138:139], 0, s[14:15]
	global_load_lds_dwordx4 v[164:165], off
	ds_read_b128 v[204:207], v0 offset:12288
	v_add3_u32 v155, s13, v150, v149
	v_add_u32_e32 v155, v155, v153
	v_add3_u32 v0, s13, v147, v149
	v_add_u32_e32 v0, v0, v153
	ds_read_b128 v[156:159], v155 offset:32768
	ds_read_b128 v[160:163], v155 offset:36864
	s_waitcnt lgkmcnt(5)
	v_mfma_f32_32x32x16_bf16 v[114:129], v[192:195], v[208:211], v[114:129]
	v_mfma_f32_32x32x16_bf16 v[98:113], v[192:195], v[212:215], v[98:113]
	ds_read_b128 v[192:195], v0
	s_waitcnt lgkmcnt(5)
	v_mfma_f32_32x32x16_bf16 v[82:97], v[196:199], v[208:211], v[82:97]
	v_mfma_f32_32x32x16_bf16 v[66:81], v[196:199], v[212:215], v[66:81]
	ds_read_b128 v[196:199], v0 offset:4096
	s_waitcnt lgkmcnt(5)
	v_mfma_f32_32x32x16_bf16 v[50:65], v[200:203], v[208:211], v[50:65]
	v_mfma_f32_32x32x16_bf16 v[34:49], v[200:203], v[212:215], v[34:49]
	ds_read_b128 v[200:203], v0 offset:8192
	s_waitcnt lgkmcnt(5)
	v_mfma_f32_32x32x16_bf16 v[18:33], v[204:207], v[208:211], v[18:33]
	v_mfma_f32_32x32x16_bf16 v[2:17], v[204:207], v[212:215], v[2:17]
	ds_read_b128 v[204:207], v0 offset:12288
	v_add3_u32 v155, s13, v150, v149
	v_add_u32_e32 v155, v155, v154
	v_add3_u32 v0, s13, v147, v149
	v_add_u32_e32 v0, v0, v154
	ds_read_b128 v[208:211], v155 offset:32768
	ds_read_b128 v[212:215], v155 offset:36864
	s_waitcnt lgkmcnt(5)
	v_mfma_f32_32x32x16_bf16 v[114:129], v[192:195], v[156:159], v[114:129]
	v_mfma_f32_32x32x16_bf16 v[98:113], v[192:195], v[160:163], v[98:113]
	ds_read_b128 v[192:195], v0
	s_waitcnt lgkmcnt(5)
	v_mfma_f32_32x32x16_bf16 v[82:97], v[196:199], v[156:159], v[82:97]
	v_mfma_f32_32x32x16_bf16 v[66:81], v[196:199], v[160:163], v[66:81]
	ds_read_b128 v[196:199], v0 offset:4096
	s_waitcnt lgkmcnt(5)
	v_mfma_f32_32x32x16_bf16 v[50:65], v[200:203], v[156:159], v[50:65]
	v_mfma_f32_32x32x16_bf16 v[34:49], v[200:203], v[160:163], v[34:49]
	ds_read_b128 v[200:203], v0 offset:8192
	s_waitcnt lgkmcnt(5)
	v_mfma_f32_32x32x16_bf16 v[18:33], v[204:207], v[156:159], v[18:33]
	v_mfma_f32_32x32x16_bf16 v[2:17], v[204:207], v[160:163], v[2:17]
	ds_read_b128 v[204:207], v0 offset:12288
	s_waitcnt lgkmcnt(3)
	v_mfma_f32_32x32x16_bf16 v[114:129], v[192:195], v[208:211], v[114:129]
	v_mfma_f32_32x32x16_bf16 v[98:113], v[192:195], v[212:215], v[98:113]
	s_waitcnt lgkmcnt(0)
	s_waitcnt vmcnt(0)
	s_barrier
	v_add3_u32 v155, s12, v150, v149
	v_add_u32_e32 v155, v155, v151
	v_add3_u32 v0, s12, v147, v149
	v_add_u32_e32 v0, v0, v151
	ds_read_b128 v[156:159], v155 offset:32768
	ds_read_b128 v[160:163], v155 offset:36864
	ds_read_b128 v[192:195], v0
	v_mfma_f32_32x32x16_bf16 v[82:97], v[196:199], v[208:211], v[82:97]
	v_mfma_f32_32x32x16_bf16 v[66:81], v[196:199], v[212:215], v[66:81]
	ds_read_b128 v[196:199], v0 offset:4096
	v_mfma_f32_32x32x16_bf16 v[50:65], v[200:203], v[208:211], v[50:65]
	v_mfma_f32_32x32x16_bf16 v[34:49], v[200:203], v[212:215], v[34:49]
	ds_read_b128 v[200:203], v0 offset:8192
	v_mfma_f32_32x32x16_bf16 v[18:33], v[204:207], v[208:211], v[18:33]
	v_mfma_f32_32x32x16_bf16 v[2:17], v[204:207], v[212:215], v[2:17]
	ds_read_b128 v[204:207], v0 offset:12288
	s_xor_b32 s13, s9, 1
	s_add_u32 s4, s4, 0x80
	s_addc_u32 s5, s5, 0
	s_cmpk_eq_i32 s4, 0xb80
	s_cbranch_scc0 .LBB0_461
	s_waitcnt lgkmcnt(0)
	s_andn2_b64 vcc, exec, s[2:3]
	s_lshl_b32 s2, s13, 16
	s_cbranch_vccnz .LBB0_453
	v_add_u32_e32 v0, s8, v142
	s_xor_b32 s3, s2, 0x10000
	v_mad_i64_i32 v[138:139], s[4:5], v0, s37, v[130:131]
	v_add_u32_e32 v0, s3, v143
	v_add_u32_e32 v136, s7, v142
	v_add_u32_e32 v155, 0x8000, v0
	v_readfirstlane_b32 s3, v0
	v_mad_i64_i32 v[136:137], s[4:5], v136, s37, v[132:133]
	s_mov_b32 m0, s3
	v_readfirstlane_b32 s3, v155
	v_add_u32_e32 v155, 0x2000, v0
	global_load_lds_dwordx4 v[138:139], off
	s_mov_b32 m0, s3
	s_mov_b64 s[4:5], 0x30000
	v_readfirstlane_b32 s3, v155
	v_add_u32_e32 v155, 0xa000, v0
	global_load_lds_dwordx4 v[136:137], off
	v_lshl_add_u64 v[156:157], v[138:139], 0, s[4:5]
	s_mov_b32 m0, s3
	v_readfirstlane_b32 s3, v155
	v_add_u32_e32 v155, 0x4000, v0
	global_load_lds_dwordx4 v[156:157], off
	v_lshl_add_u64 v[156:157], v[136:137], 0, s[4:5]
	s_mov_b32 m0, s3
	s_mov_b64 s[4:5], 0x60000
	v_readfirstlane_b32 s3, v155
	v_add_u32_e32 v155, 0xc000, v0
	global_load_lds_dwordx4 v[156:157], off
	v_lshl_add_u64 v[156:157], v[138:139], 0, s[4:5]
	s_mov_b32 m0, s3
	v_readfirstlane_b32 s3, v155
	v_add_u32_e32 v155, 0x6000, v0
	global_load_lds_dwordx4 v[156:157], off
	v_lshl_add_u64 v[156:157], v[136:137], 0, s[4:5]
	s_mov_b32 m0, s3
	s_mov_b64 s[4:5], 0x90000
	v_readfirstlane_b32 s3, v155
	v_add_u32_e32 v0, 0xe000, v0
	global_load_lds_dwordx4 v[156:157], off
	v_lshl_add_u64 v[138:139], v[138:139], 0, s[4:5]
	s_mov_b32 m0, s3
	v_readfirstlane_b32 s3, v0
	global_load_lds_dwordx4 v[138:139], off
	v_lshl_add_u64 v[136:137], v[136:137], 0, s[4:5]
	s_mov_b32 m0, s3
	s_nop 0
	global_load_lds_dwordx4 v[136:137], off
	s_branch .LBB0_453

; template <int EPI, int AMAP, int KOFFMODE, int K>
; __device__ __forceinline__ void gemm_phase(unsigned char* smem, const bf16_t* A, int lda, const bf16_t* Bt, int NT, const EpiArgs& ea) {
;     ...
;         f32x16 acc[4][2];
; #pragma unroll
;         for (int i = 0; i < 4; ++i)
; #pragma unroll
;             for (int j = 0; j < 2; ++j)
; #pragma unroll
;                 for (int r = 0; r < 16; ++r) acc[i][j][r] = 0.f;
;         for (int kt = 0; kt < nk; ++kt) {
;             if (kt + 1 < nk) GEMM_DMA(m0, n0, kt + 1, cur ^ 1);
;             else if (have_next) GEMM_DMA(m0n, n0n, 0, cur ^ 1);
;             const unsigned char* Ac = smem + cur * STGB + (wm * 128 + l31) * 128;
;             const unsigned char* Bc = smem + cur * STGB + 32768 + (wn * 64 + l31) * 128;
;             bf16x8 fa[2][4], fb[2][2];
;             fb[0][0] = *(const bf16x8*)(Bc + (((0) ^ yz) & 7) * 16);
;             fb[0][1] = *(const bf16x8*)(Bc + 32 * 128 + (((0) ^ yz) & 7) * 16);
; #pragma unroll
;             for (int i = 0; i < 4; ++i) fa[0][i] = *(const bf16x8*)(Ac + i * 32 * 128 + (((0) ^ yz) & 7) * 16);
; #pragma unroll
;             for (int s = 0; s < 4; ++s) {
;                 if (s < 3) {
;                     const int o_ = (((2 * (s + 1)) ^ yz) & 7) * 16;
;                     fb[(s + 1) & 1][0] = *(const bf16x8*)(Bc + o_);
;                     fb[(s + 1) & 1][1] = *(const bf16x8*)(Bc + 32 * 128 + o_);
; #pragma unroll
;                     for (int i = 0; i < 4; ++i) fa[(s + 1) & 1][i] = *(const bf16x8*)(Ac + i * 32 * 128 + o_);
;                 }
; #pragma unroll
;                 for (int i = 0; i < 4; ++i) {
;                     acc[i][0] = __builtin_amdgcn_mfma_f32_32x32x16_bf16(fa[s & 1][i], fb[s & 1][0], acc[i][0], 0, 0, 0);
;                     acc[i][1] = __builtin_amdgcn_mfma_f32_32x32x16_bf16(fa[s & 1][i], fb[s & 1][1], acc[i][1], 0, 0, 0);
;                 }
;                 __builtin_amdgcn_sched_barrier(0);
;             }
;             if (kt + 1 < nk) asm volatile("s_waitcnt vmcnt(0)" ::: "memory");
;             __builtin_amdgcn_s_barrier();
;             cur ^= 1;
;         }
.LBB0_1428:
	v_add_u32_e32 v2, s10, v142
	v_ashrrev_i32_e32 v3, 31, v2
	v_lshlrev_b64 v[2:3], 11, v[2:3]
	v_lshl_add_u64 v[136:137], v[134:135], 0, v[2:3]
	v_add_u32_e32 v2, s11, v142
	v_ashrrev_i32_e32 v3, 31, v2
	v_lshlrev_b64 v[2:3], 11, v[2:3]
	v_lshl_add_u64 v[138:139], v[134:135], 0, v[2:3]
	v_mov_b32_e32 v2, 0
	s_mov_b64 s[4:5], 0
	s_mov_b32 s13, s9
	v_mov_b32_e32 v3, v2
	v_mov_b32_e32 v4, v2
	v_mov_b32_e32 v5, v2
	v_mov_b32_e32 v6, v2
	v_mov_b32_e32 v7, v2
	v_mov_b32_e32 v8, v2
	v_mov_b32_e32 v9, v2
	v_mov_b32_e32 v10, v2
	v_mov_b32_e32 v11, v2
	v_mov_b32_e32 v12, v2
	v_mov_b32_e32 v13, v2
	v_mov_b32_e32 v14, v2
	v_mov_b32_e32 v15, v2
	v_mov_b32_e32 v16, v2
	v_mov_b32_e32 v17, v2
	v_mov_b32_e32 v18, v2
	v_mov_b32_e32 v19, v2
	v_mov_b32_e32 v20, v2
	v_mov_b32_e32 v21, v2
	v_mov_b32_e32 v22, v2
	v_mov_b32_e32 v23, v2
	v_mov_b32_e32 v24, v2
	v_mov_b32_e32 v25, v2
	v_mov_b32_e32 v26, v2
	v_mov_b32_e32 v27, v2
	v_mov_b32_e32 v28, v2
	v_mov_b32_e32 v29, v2
	v_mov_b32_e32 v30, v2
	v_mov_b32_e32 v31, v2
	v_mov_b32_e32 v32, v2
	v_mov_b32_e32 v33, v2
	v_mov_b32_e32 v34, v2
	v_mov_b32_e32 v35, v2
	v_mov_b32_e32 v36, v2
	v_mov_b32_e32 v37, v2
	v_mov_b32_e32 v38, v2
	v_mov_b32_e32 v39, v2
	v_mov_b32_e32 v40, v2
	v_mov_b32_e32 v41, v2
	v_mov_b32_e32 v42, v2
	v_mov_b32_e32 v43, v2
	v_mov_b32_e32 v44, v2
	v_mov_b32_e32 v45, v2
	v_mov_b32_e32 v46, v2
	v_mov_b32_e32 v47, v2
	v_mov_b32_e32 v48, v2
	v_mov_b32_e32 v49, v2
	v_mov_b32_e32 v50, v2
	v_mov_b32_e32 v51, v2
	v_mov_b32_e32 v52, v2
	v_mov_b32_e32 v53, v2
	v_mov_b32_e32 v54, v2
	v_mov_b32_e32 v55, v2
	v_mov_b32_e32 v56, v2
	v_mov_b32_e32 v57, v2
	v_mov_b32_e32 v58, v2
	v_mov_b32_e32 v59, v2
	v_mov_b32_e32 v60, v2
	v_mov_b32_e32 v61, v2
	v_mov_b32_e32 v62, v2
	v_mov_b32_e32 v63, v2
	v_mov_b32_e32 v64, v2
	v_mov_b32_e32 v65, v2
	v_mov_b32_e32 v66, v2
	v_mov_b32_e32 v67, v2
	v_mov_b32_e32 v68, v2
	v_mov_b32_e32 v69, v2
	v_mov_b32_e32 v70, v2
	v_mov_b32_e32 v71, v2
	v_mov_b32_e32 v72, v2
	v_mov_b32_e32 v73, v2
	v_mov_b32_e32 v74, v2
	v_mov_b32_e32 v75, v2
	v_mov_b32_e32 v76, v2
	v_mov_b32_e32 v77, v2
	v_mov_b32_e32 v78, v2
	v_mov_b32_e32 v79, v2
	v_mov_b32_e32 v80, v2
	v_mov_b32_e32 v81, v2
	v_mov_b32_e32 v82, v2
	v_mov_b32_e32 v83, v2
	v_mov_b32_e32 v84, v2
	v_mov_b32_e32 v85, v2
	v_mov_b32_e32 v86, v2
	v_mov_b32_e32 v87, v2
	v_mov_b32_e32 v88, v2
	v_mov_b32_e32 v89, v2
	v_mov_b32_e32 v90, v2
	v_mov_b32_e32 v91, v2
	v_mov_b32_e32 v92, v2
	v_mov_b32_e32 v93, v2
	v_mov_b32_e32 v94, v2
	v_mov_b32_e32 v95, v2
	v_mov_b32_e32 v96, v2
	v_mov_b32_e32 v97, v2
	v_mov_b32_e32 v98, v2
	v_mov_b32_e32 v99, v2
	v_mov_b32_e32 v100, v2
	v_mov_b32_e32 v101, v2
	v_mov_b32_e32 v102, v2
	v_mov_b32_e32 v103, v2
	v_mov_b32_e32 v104, v2
	v_mov_b32_e32 v105, v2
	v_mov_b32_e32 v106, v2
	v_mov_b32_e32 v107, v2
	v_mov_b32_e32 v108, v2
	v_mov_b32_e32 v109, v2
	v_mov_b32_e32 v110, v2
	v_mov_b32_e32 v111, v2
	v_mov_b32_e32 v112, v2
	v_mov_b32_e32 v113, v2
	v_mov_b32_e32 v114, v2
	v_mov_b32_e32 v115, v2
	v_mov_b32_e32 v116, v2
	v_mov_b32_e32 v117, v2
	v_mov_b32_e32 v118, v2
	v_mov_b32_e32 v119, v2
	v_mov_b32_e32 v120, v2
	v_mov_b32_e32 v121, v2
	v_mov_b32_e32 v122, v2
	v_mov_b32_e32 v123, v2
	v_mov_b32_e32 v124, v2
	v_mov_b32_e32 v125, v2
	v_mov_b32_e32 v126, v2
	v_mov_b32_e32 v127, v2
	v_mov_b32_e32 v128, v2
	v_mov_b32_e32 v129, v2
	s_mov_b64 s[20:21], 0x800080
	s_mov_b64 s[68:69], 0x840080
	s_lshl_b32 vcc_lo, s13, 16
	v_add3_u32 v155, vcc_lo, v150, v149
	v_add_u32_e32 v155, v155, v151
	v_add3_u32 v0, vcc_lo, v147, v149
	v_add_u32_e32 v0, v0, v151
	ds_read_b128 v[156:159], v155 offset:32768
	ds_read_b128 v[160:163], v155 offset:36864
	ds_read_b128 v[192:195], v0
	ds_read_b128 v[196:199], v0 offset:4096
	ds_read_b128 v[200:203], v0 offset:8192
	ds_read_b128 v[204:207], v0 offset:12288
.LBB0_1429:
	s_mov_b32 s9, s13
	s_lshl_b32 s13, s9, 16
	s_xor_b32 s12, s13, 0x10000
	v_readfirstlane_b32 vcc_lo, v143
	s_nop 0
	s_add_u32 vcc_lo, vcc_lo, s12
	v_add3_u32 v155, s13, v150, v149
	v_add_u32_e32 v155, v155, v152
	v_add3_u32 v0, s13, v147, v149
	v_add_u32_e32 v0, v0, v152
	ds_read_b128 v[208:211], v155 offset:32768
	ds_read_b128 v[212:215], v155 offset:36864
	s_waitcnt lgkmcnt(5)
	v_mfma_f32_32x32x16_bf16 v[114:129], v[192:195], v[156:159], v[114:129]
	s_add_u32 s14, s4, 0xe380080
	s_addc_u32 s15, s5, 0
	s_mov_b32 m0, vcc_lo
	v_lshl_add_u64 v[164:165], v[136:137], 0, s[14:15]
	global_load_lds_dwordx4 v[164:165], off
	v_mfma_f32_32x32x16_bf16 v[98:113], v[192:195], v[160:163], v[98:113]
	s_add_u32 s14, s4, 0xe3a0080
	s_addc_u32 s15, s5, 0
	s_add_u32 m0, vcc_lo, 0x2000
	v_lshl_add_u64 v[164:165], v[136:137], 0, s[14:15]
	global_load_lds_dwordx4 v[164:165], off
	ds_read_b128 v[192:195], v0
	s_waitcnt lgkmcnt(5)
	v_mfma_f32_32x32x16_bf16 v[82:97], v[196:199], v[156:159], v[82:97]
	s_add_u32 s14, s4, 0xe3c0080
	s_addc_u32 s15, s5, 0
	s_add_u32 m0, vcc_lo, 0x4000
	v_lshl_add_u64 v[164:165], v[136:137], 0, s[14:15]
	global_load_lds_dwordx4 v[164:165], off
	v_mfma_f32_32x32x16_bf16 v[66:81], v[196:199], v[160:163], v[66:81]
	s_add_u32 s14, s4, 0xe3e0080
	s_addc_u32 s15, s5, 0
	s_add_u32 m0, vcc_lo, 0x6000
	v_lshl_add_u64 v[164:165], v[136:137], 0, s[14:15]
	global_load_lds_dwordx4 v[164:165], off
	ds_read_b128 v[196:199], v0 offset:4096
	s_waitcnt lgkmcnt(5)
	v_mfma_f32_32x32x16_bf16 v[50:65], v[200:203], v[156:159], v[50:65]
	s_add_u32 s14, s4, s20
	s_addc_u32 s15, s5, s21
	s_add_u32 m0, vcc_lo, 0x8000
	v_lshl_add_u64 v[164:165], v[138:139], 0, s[14:15]
	global_load_lds_dwordx4 v[164:165], off
	v_mfma_f32_32x32x16_bf16 v[34:49], v[200:203], v[160:163], v[34:49]
	s_add_u32 s14, s4, 0x820080
	s_addc_u32 s15, s5, 0
	s_add_u32 m0, vcc_lo, 0xa000
	v_lshl_add_u64 v[164:165], v[138:139], 0, s[14:15]
	global_load_lds_dwordx4 v[164:165], off
	ds_read_b128 v[200:203], v0 offset:8192
	s_waitcnt lgkmcnt(5)
; template <int EPI, int AMAP, int KOFFMODE, int K>
; __device__ __forceinline__ void gemm_phase(unsigned char* smem, const bf16_t* A, int lda, const bf16_t* Bt, int NT, const EpiArgs& ea) {
;     ...
;         for (int kt = 0; kt < nk; ++kt) {
;             if (kt + 1 < nk) GEMM_DMA(m0, n0, kt + 1, cur ^ 1);
;             else if (have_next) GEMM_DMA(m0n, n0n, 0, cur ^ 1);
;             const unsigned char* Ac = smem + cur * STGB + (wm * 128 + l31) * 128;
;             const unsigned char* Bc = smem + cur * STGB + 32768 + (wn * 64 + l31) * 128;
;             bf16x8 fa[2][4], fb[2][2];
;             fb[0][0] = *(const bf16x8*)(Bc + (((0) ^ yz) & 7) * 16);
;             fb[0][1] = *(const bf16x8*)(Bc + 32 * 128 + (((0) ^ yz) & 7) * 16);
; #pragma unroll
;             for (int i = 0; i < 4; ++i) fa[0][i] = *(const bf16x8*)(Ac + i * 32 * 128 + (((0) ^ yz) & 7) * 16);
; #pragma unroll
;             for (int s = 0; s < 4; ++s) {
;                 if (s < 3) {
;                     const int o_ = (((2 * (s + 1)) ^ yz) & 7) * 16;
;                     fb[(s + 1) & 1][0] = *(const bf16x8*)(Bc + o_);
;                     fb[(s + 1) & 1][1] = *(const bf16x8*)(Bc + 32 * 128 + o_);
; #pragma unroll
;                     for (int i = 0; i < 4; ++i) fa[(s + 1) & 1][i] = *(const bf16x8*)(Ac + i * 32 * 128 + o_);
;                 }
; #pragma unroll
;                 for (int i = 0; i < 4; ++i) {
;                     acc[i][0] = __builtin_amdgcn_mfma_f32_32x32x16_bf16(fa[s & 1][i], fb[s & 1][0], acc[i][0], 0, 0, 0);
;                     acc[i][1] = __builtin_amdgcn_mfma_f32_32x32x16_bf16(fa[s & 1][i], fb[s & 1][1], acc[i][1], 0, 0, 0);
;                 }
;                 __builtin_amdgcn_sched_barrier(0);
;             }
;             if (kt + 1 < nk) asm volatile("s_waitcnt vmcnt(0)" ::: "memory");
;             __builtin_amdgcn_s_barrier();
;             cur ^= 1;
;         }
	v_mfma_f32_32x32x16_bf16 v[18:33], v[204:207], v[156:159], v[18:33]
	s_add_u32 s14, s4, s68
	s_addc_u32 s15, s5, s69
	s_add_u32 m0, vcc_lo, 0xc000
	v_lshl_add_u64 v[164:165], v[138:139], 0, s[14:15]
	global_load_lds_dwordx4 v[164:165], off
	v_mfma_f32_32x32x16_bf16 v[2:17], v[204:207], v[160:163], v[2:17]
	s_add_u32 s14, s4, 0x860080
	s_addc_u32 s15, s5, 0
	s_add_u32 m0, vcc_lo, 0xe000
	v_lshl_add_u64 v[164:165], v[138:139], 0, s[14:15]
	global_load_lds_dwordx4 v[164:165], off
	ds_read_b128 v[204:207], v0 offset:12288
	v_add3_u32 v155, s13, v150, v149
	v_add_u32_e32 v155, v155, v153
	v_add3_u32 v0, s13, v147, v149
	v_add_u32_e32 v0, v0, v153
	ds_read_b128 v[156:159], v155 offset:32768
	ds_read_b128 v[160:163], v155 offset:36864
	s_waitcnt lgkmcnt(5)
	v_mfma_f32_32x32x16_bf16 v[114:129], v[192:195], v[208:211], v[114:129]
	v_mfma_f32_32x32x16_bf16 v[98:113], v[192:195], v[212:215], v[98:113]
	ds_read_b128 v[192:195], v0
	s_waitcnt lgkmcnt(5)
	v_mfma_f32_32x32x16_bf16 v[82:97], v[196:199], v[208:211], v[82:97]
	v_mfma_f32_32x32x16_bf16 v[66:81], v[196:199], v[212:215], v[66:81]
	ds_read_b128 v[196:199], v0 offset:4096
	s_waitcnt lgkmcnt(5)
	v_mfma_f32_32x32x16_bf16 v[50:65], v[200:203], v[208:211], v[50:65]
	v_mfma_f32_32x32x16_bf16 v[34:49], v[200:203], v[212:215], v[34:49]
	ds_read_b128 v[200:203], v0 offset:8192
	s_waitcnt lgkmcnt(5)
	v_mfma_f32_32x32x16_bf16 v[18:33], v[204:207], v[208:211], v[18:33]
	v_mfma_f32_32x32x16_bf16 v[2:17], v[204:207], v[212:215], v[2:17]
	ds_read_b128 v[204:207], v0 offset:12288
	v_add3_u32 v155, s13, v150, v149
	v_add_u32_e32 v155, v155, v154
	v_add3_u32 v0, s13, v147, v149
	v_add_u32_e32 v0, v0, v154
	ds_read_b128 v[208:211], v155 offset:32768
	ds_read_b128 v[212:215], v155 offset:36864
	s_waitcnt lgkmcnt(5)
	v_mfma_f32_32x32x16_bf16 v[114:129], v[192:195], v[156:159], v[114:129]
	v_mfma_f32_32x32x16_bf16 v[98:113], v[192:195], v[160:163], v[98:113]
	ds_read_b128 v[192:195], v0
	s_waitcnt lgkmcnt(5)
	v_mfma_f32_32x32x16_bf16 v[82:97], v[196:199], v[156:159], v[82:97]
	v_mfma_f32_32x32x16_bf16 v[66:81], v[196:199], v[160:163], v[66:81]
	ds_read_b128 v[196:199], v0 offset:4096
	s_waitcnt lgkmcnt(5)
	v_mfma_f32_32x32x16_bf16 v[50:65], v[200:203], v[156:159], v[50:65]
	v_mfma_f32_32x32x16_bf16 v[34:49], v[200:203], v[160:163], v[34:49]
	ds_read_b128 v[200:203], v0 offset:8192
	s_waitcnt lgkmcnt(5)
	v_mfma_f32_32x32x16_bf16 v[18:33], v[204:207], v[156:159], v[18:33]
	v_mfma_f32_32x32x16_bf16 v[2:17], v[204:207], v[160:163], v[2:17]
	ds_read_b128 v[204:207], v0 offset:12288
	s_waitcnt lgkmcnt(3)
	v_mfma_f32_32x32x16_bf16 v[114:129], v[192:195], v[208:211], v[114:129]
	v_mfma_f32_32x32x16_bf16 v[98:113], v[192:195], v[212:215], v[98:113]
	s_waitcnt lgkmcnt(0)
	s_waitcnt vmcnt(0)
	s_barrier
	v_add3_u32 v155, s12, v150, v149
	v_add_u32_e32 v155, v155, v151
	v_add3_u32 v0, s12, v147, v149
	v_add_u32_e32 v0, v0, v151
	ds_read_b128 v[156:159], v155 offset:32768
	ds_read_b128 v[160:163], v155 offset:36864
	ds_read_b128 v[192:195], v0
	v_mfma_f32_32x32x16_bf16 v[82:97], v[196:199], v[208:211], v[82:97]
	v_mfma_f32_32x32x16_bf16 v[66:81], v[196:199], v[212:215], v[66:81]
	ds_read_b128 v[196:199], v0 offset:4096
	v_mfma_f32_32x32x16_bf16 v[50:65], v[200:203], v[208:211], v[50:65]
	v_mfma_f32_32x32x16_bf16 v[34:49], v[200:203], v[212:215], v[34:49]
	ds_read_b128 v[200:203], v0 offset:8192
	v_mfma_f32_32x32x16_bf16 v[18:33], v[204:207], v[208:211], v[18:33]
	v_mfma_f32_32x32x16_bf16 v[2:17], v[204:207], v[212:215], v[2:17]
	ds_read_b128 v[204:207], v0 offset:12288
	s_xor_b32 s13, s9, 1
	s_add_u32 s4, s4, 0x80
	s_addc_u32 s5, s5, 0
	s_cmpk_eq_i32 s4, 0x780
	s_cbranch_scc0 .LBB0_1429
	s_waitcnt lgkmcnt(0)
	s_andn2_b64 vcc, exec, s[2:3]
	s_lshl_b32 s2, s13, 16
	s_cbranch_vccnz .LBB0_1421
	v_add_u32_e32 v136, s8, v142
	s_xor_b32 s3, s2, 0x10000
	v_ashrrev_i32_e32 v137, 31, v136
	v_add_u32_e32 v138, s7, v142
	v_add_u32_e32 v0, s3, v143
	v_lshlrev_b64 v[136:137], 11, v[136:137]
	v_ashrrev_i32_e32 v139, 31, v138
	v_add_u32_e32 v155, 0x8000, v0
	v_readfirstlane_b32 s3, v0
	v_lshlrev_b64 v[138:139], 11, v[138:139]
	v_lshl_add_u64 v[136:137], v[130:131], 0, v[136:137]
	s_mov_b32 m0, s3
	v_readfirstlane_b32 s3, v155
	v_add_u32_e32 v155, 0x2000, v0
	v_lshl_add_u64 v[138:139], v[132:133], 0, v[138:139]
	global_load_lds_dwordx4 v[136:137], off
	s_mov_b32 m0, s3
	s_mov_b64 s[4:5], 0x20000
	v_readfirstlane_b32 s3, v155
	v_add_u32_e32 v155, 0xa000, v0
	global_load_lds_dwordx4 v[138:139], off
	v_lshl_add_u64 v[156:157], v[136:137], 0, s[4:5]
	s_mov_b32 m0, s3
	v_readfirstlane_b32 s3, v155
	v_add_u32_e32 v155, 0x4000, v0
	global_load_lds_dwordx4 v[156:157], off
	v_lshl_add_u64 v[156:157], v[138:139], 0, s[4:5]
	s_mov_b32 m0, s3
	s_mov_b64 s[4:5], 0x40000
	v_readfirstlane_b32 s3, v155
	v_add_u32_e32 v155, 0xc000, v0
	global_load_lds_dwordx4 v[156:157], off
	v_lshl_add_u64 v[156:157], v[136:137], 0, s[4:5]
	s_mov_b32 m0, s3
	v_readfirstlane_b32 s3, v155
	v_add_u32_e32 v155, 0x6000, v0
	global_load_lds_dwordx4 v[156:157], off
	v_lshl_add_u64 v[156:157], v[138:139], 0, s[4:5]
	s_mov_b32 m0, s3
	s_mov_b64 s[4:5], 0x60000
	v_readfirstlane_b32 s3, v155
	v_add_u32_e32 v0, 0xe000, v0
	global_load_lds_dwordx4 v[156:157], off
	v_lshl_add_u64 v[136:137], v[136:137], 0, s[4:5]
	s_mov_b32 m0, s3
	v_readfirstlane_b32 s3, v0
	global_load_lds_dwordx4 v[136:137], off
	v_lshl_add_u64 v[136:137], v[138:139], 0, s[4:5]
	s_mov_b32 m0, s3
	s_nop 0
	global_load_lds_dwordx4 v[136:137], off
	s_branch .LBB0_1421
